# EpiResid epilogues of out-proj and FFN-down GEMMs: batched residual/stat loads per column group (4 waits instead of 32 serialized round trips)
# speedup vs baseline: 1.1454x; 1.0046x over previous
.LBB0_1387:
	v_min_i32_e32 v130, 64, v142
	v_ashrrev_i32_e32 v130, 4, v130
	s_mov_b32 s8, 0xc000
	v_mul_hi_i32 v131, v130, s8
	v_mul_lo_u32 v130, v130, s8
	v_mov_b32_e32 v132, v180
	s_mov_b32 s10, s47
	v_mov_b32_e32 v143, v181
	s_mov_b32 s40, s37
	v_lshl_add_u64 v[130:131], s[22:23], 0, v[130:131]
	s_mov_b64 s[8:9], 0x4000
	v_lshl_add_u64 v[160:161], v[130:131], 0, s[8:9]
	v_lshlrev_b32_e32 v130, 8, v136
	s_lshl_b32 s8, s10, 5
	v_add_u32_e32 v130, s8, v130
	v_lshl_add_u32 v162, v132, 2, v130
	v_ashrrev_i32_e32 v163, 31, v162
	v_cmp_gt_i32_e64 s[10:11], 64, v142
	v_lshlrev_b32_e32 v142, 8, v142
	v_lshlrev_b32_e64 v144, 6, s40
	v_add3_u32 v176, v143, v142, v144
	s_and_b64 s[38:39], s[10:11], exec
	s_cselect_b32 s39, s13, s54
	s_cselect_b32 s38, s12, s51
	s_and_b64 s[10:11], s[10:11], exec
	v_readlane_b32 s10, v255, 18
	s_cselect_b32 s11, s15, s10
	v_readlane_b32 s10, v255, 17
	s_cselect_b32 s10, s14, s10
	v_lshlrev_b32_e32 v234, 2, v162
	v_lshl_add_u32 v196, v176, 13, v234
	v_add_u32_e32 v197, 0x20000, v196
	v_add_u32_e32 v198, 0x40000, v196
	v_add_u32_e32 v199, 0x60000, v196
	v_add_u32_e32 v200, 0x100000, v196
	v_add_u32_e32 v201, 0x120000, v196
	v_add_u32_e32 v202, 0x140000, v196
	v_add_u32_e32 v203, 0x160000, v196
	v_lshlrev_b32_e32 v235, 3, v176
	v_lshl_add_u64 v[236:237], v[162:163], 2, v[160:161]
	s_and_b64 vcc, exec, s[26:27]
	s_nop 4
	s_cbranch_vccz .Lp6epi_nostats
.Lp6epi_stats:
	global_load_dwordx2 v[214:215], v235, s[16:17]
	global_load_dwordx2 v[216:217], v235, s[16:17] offset:128
	global_load_dwordx2 v[218:219], v235, s[16:17] offset:256
	global_load_dwordx2 v[220:221], v235, s[16:17] offset:384
	global_load_dwordx2 v[222:223], v235, s[16:17] offset:1024
	global_load_dwordx2 v[224:225], v235, s[16:17] offset:1152
	global_load_dwordx2 v[226:227], v235, s[16:17] offset:1280
	global_load_dwordx2 v[228:229], v235, s[16:17] offset:1408
	global_load_dwordx4 v[130:133], v[236:237], off
	global_load_dwordx4 v[134:137], v234, s[18:19]
	global_load_dwordx4 v[138:141], v234, s[6:7]
	global_load_dwordx4 v[164:167], v196, s[38:39]
	global_load_dwordx4 v[168:171], v197, s[38:39]
	global_load_dwordx4 v[172:175], v198, s[38:39]
	global_load_dwordx4 v[176:179], v199, s[38:39]
	global_load_dwordx4 v[184:187], v200, s[38:39]
	global_load_dwordx4 v[188:191], v201, s[38:39]
	global_load_dwordx4 v[192:195], v202, s[38:39]
	global_load_dwordx4 v[230:233], v203, s[38:39]
	s_waitcnt vmcnt(0)
	v_sub_f32_e32 v167, v167, v214
	v_sub_f32_e32 v166, v166, v214
	v_sub_f32_e32 v165, v165, v214
	v_sub_f32_e32 v164, v164, v214
	v_pk_mul_f32 v[164:165], v[214:215], v[164:165] op_sel:[1,0]
	v_pk_mul_f32 v[166:167], v[214:215], v[166:167] op_sel:[1,0]
	v_pk_fma_f32 v[164:165], v[134:135], v[164:165], v[138:139]
	v_pk_fma_f32 v[166:167], v[136:137], v[166:167], v[140:141]
	v_pk_mul_f32 v[166:167], v[166:167], s[88:89] op_sel_hi:[1,0]
	v_pk_mul_f32 v[164:165], v[164:165], s[88:89] op_sel_hi:[1,0]
	v_pk_fma_f32 v[128:129], v[128:129], v[132:133], v[166:167]
	v_pk_fma_f32 v[126:127], v[126:127], v[130:131], v[164:165]
	global_store_dwordx4 v196, v[126:129], s[10:11]
	s_nop 1
	global_load_dwordx4 v[126:129], v196, s[38:39] offset:64
	v_sub_f32_e32 v171, v171, v216
	v_sub_f32_e32 v170, v170, v216
	v_sub_f32_e32 v169, v169, v216
	v_sub_f32_e32 v168, v168, v216
	v_pk_mul_f32 v[168:169], v[216:217], v[168:169] op_sel:[1,0]
	v_pk_mul_f32 v[170:171], v[216:217], v[170:171] op_sel:[1,0]
	v_pk_fma_f32 v[168:169], v[134:135], v[168:169], v[138:139]
	v_pk_fma_f32 v[170:171], v[136:137], v[170:171], v[140:141]
	v_pk_mul_f32 v[170:171], v[170:171], s[88:89] op_sel_hi:[1,0]
	v_pk_mul_f32 v[168:169], v[168:169], s[88:89] op_sel_hi:[1,0]
	v_pk_fma_f32 v[124:125], v[124:125], v[132:133], v[170:171]
	v_pk_fma_f32 v[122:123], v[122:123], v[130:131], v[168:169]
	global_store_dwordx4 v197, v[122:125], s[10:11]
	s_nop 1
	global_load_dwordx4 v[122:125], v197, s[38:39] offset:64
	v_sub_f32_e32 v175, v175, v218
	v_sub_f32_e32 v174, v174, v218
	v_sub_f32_e32 v173, v173, v218
	v_sub_f32_e32 v172, v172, v218
	v_pk_mul_f32 v[172:173], v[218:219], v[172:173] op_sel:[1,0]
	v_pk_mul_f32 v[174:175], v[218:219], v[174:175] op_sel:[1,0]
	v_pk_fma_f32 v[172:173], v[134:135], v[172:173], v[138:139]
	v_pk_fma_f32 v[174:175], v[136:137], v[174:175], v[140:141]
	v_pk_mul_f32 v[174:175], v[174:175], s[88:89] op_sel_hi:[1,0]
	v_pk_mul_f32 v[172:173], v[172:173], s[88:89] op_sel_hi:[1,0]
	v_pk_fma_f32 v[120:121], v[120:121], v[132:133], v[174:175]
	v_pk_fma_f32 v[118:119], v[118:119], v[130:131], v[172:173]
	global_store_dwordx4 v198, v[118:121], s[10:11]
	s_nop 1
	global_load_dwordx4 v[118:121], v198, s[38:39] offset:64
	v_sub_f32_e32 v179, v179, v220
	v_sub_f32_e32 v178, v178, v220
	v_sub_f32_e32 v177, v177, v220
	v_sub_f32_e32 v176, v176, v220
	v_pk_mul_f32 v[176:177], v[220:221], v[176:177] op_sel:[1,0]
	v_pk_mul_f32 v[178:179], v[220:221], v[178:179] op_sel:[1,0]
	v_pk_fma_f32 v[176:177], v[134:135], v[176:177], v[138:139]
	v_pk_fma_f32 v[178:179], v[136:137], v[178:179], v[140:141]
	v_pk_mul_f32 v[178:179], v[178:179], s[88:89] op_sel_hi:[1,0]
	v_pk_mul_f32 v[176:177], v[176:177], s[88:89] op_sel_hi:[1,0]
	v_pk_fma_f32 v[116:117], v[116:117], v[132:133], v[178:179]
	v_pk_fma_f32 v[114:115], v[114:115], v[130:131], v[176:177]
	global_store_dwordx4 v199, v[114:117], s[10:11]
	s_nop 1
	global_load_dwordx4 v[114:117], v199, s[38:39] offset:64
	v_sub_f32_e32 v187, v187, v222
	v_sub_f32_e32 v186, v186, v222
	v_sub_f32_e32 v185, v185, v222
	v_sub_f32_e32 v184, v184, v222
	v_pk_mul_f32 v[184:185], v[222:223], v[184:185] op_sel:[1,0]
	v_pk_mul_f32 v[186:187], v[222:223], v[186:187] op_sel:[1,0]
	v_pk_fma_f32 v[184:185], v[134:135], v[184:185], v[138:139]
	v_pk_fma_f32 v[186:187], v[136:137], v[186:187], v[140:141]
	v_pk_mul_f32 v[186:187], v[186:187], s[88:89] op_sel_hi:[1,0]
	v_pk_mul_f32 v[184:185], v[184:185], s[88:89] op_sel_hi:[1,0]
	v_pk_fma_f32 v[112:113], v[112:113], v[132:133], v[186:187]
	v_pk_fma_f32 v[110:111], v[110:111], v[130:131], v[184:185]
	global_store_dwordx4 v200, v[110:113], s[10:11]
	s_nop 1
	global_load_dwordx4 v[110:113], v200, s[38:39] offset:64
	v_sub_f32_e32 v191, v191, v224
	v_sub_f32_e32 v190, v190, v224
	v_sub_f32_e32 v189, v189, v224
	v_sub_f32_e32 v188, v188, v224
	v_pk_mul_f32 v[188:189], v[224:225], v[188:189] op_sel:[1,0]
	v_pk_mul_f32 v[190:191], v[224:225], v[190:191] op_sel:[1,0]
	v_pk_fma_f32 v[188:189], v[134:135], v[188:189], v[138:139]
	v_pk_fma_f32 v[190:191], v[136:137], v[190:191], v[140:141]
	v_pk_mul_f32 v[190:191], v[190:191], s[88:89] op_sel_hi:[1,0]
	v_pk_mul_f32 v[188:189], v[188:189], s[88:89] op_sel_hi:[1,0]
	v_pk_fma_f32 v[108:109], v[108:109], v[132:133], v[190:191]
	v_pk_fma_f32 v[106:107], v[106:107], v[130:131], v[188:189]
	global_store_dwordx4 v201, v[106:109], s[10:11]
	s_nop 1
	global_load_dwordx4 v[106:109], v201, s[38:39] offset:64
	v_sub_f32_e32 v195, v195, v226
	v_sub_f32_e32 v194, v194, v226
	v_sub_f32_e32 v193, v193, v226
	v_sub_f32_e32 v192, v192, v226
	v_pk_mul_f32 v[192:193], v[226:227], v[192:193] op_sel:[1,0]
	v_pk_mul_f32 v[194:195], v[226:227], v[194:195] op_sel:[1,0]
	v_pk_fma_f32 v[192:193], v[134:135], v[192:193], v[138:139]
	v_pk_fma_f32 v[194:195], v[136:137], v[194:195], v[140:141]
	v_pk_mul_f32 v[194:195], v[194:195], s[88:89] op_sel_hi:[1,0]
	v_pk_mul_f32 v[192:193], v[192:193], s[88:89] op_sel_hi:[1,0]
	v_pk_fma_f32 v[104:105], v[104:105], v[132:133], v[194:195]
	v_pk_fma_f32 v[102:103], v[102:103], v[130:131], v[192:193]
	global_store_dwordx4 v202, v[102:105], s[10:11]
	s_nop 1
	global_load_dwordx4 v[102:105], v202, s[38:39] offset:64
	v_sub_f32_e32 v233, v233, v228
	v_sub_f32_e32 v232, v232, v228
	v_sub_f32_e32 v231, v231, v228
	v_sub_f32_e32 v230, v230, v228
	v_pk_mul_f32 v[230:231], v[228:229], v[230:231] op_sel:[1,0]
	v_pk_mul_f32 v[232:233], v[228:229], v[232:233] op_sel:[1,0]
	v_pk_fma_f32 v[230:231], v[134:135], v[230:231], v[138:139]
	v_pk_fma_f32 v[232:233], v[136:137], v[232:233], v[140:141]
	v_pk_mul_f32 v[232:233], v[232:233], s[88:89] op_sel_hi:[1,0]
	v_pk_mul_f32 v[230:231], v[230:231], s[88:89] op_sel_hi:[1,0]
	v_pk_fma_f32 v[100:101], v[100:101], v[132:133], v[232:233]
	v_pk_fma_f32 v[98:99], v[98:99], v[130:131], v[230:231]
	global_store_dwordx4 v203, v[98:101], s[10:11]
	s_nop 1
	global_load_dwordx4 v[98:101], v203, s[38:39] offset:64
	global_load_dwordx4 v[130:133], v[236:237], off offset:64
	global_load_dwordx4 v[134:137], v234, s[18:19] offset:64
	global_load_dwordx4 v[138:141], v234, s[6:7] offset:64
	s_waitcnt vmcnt(0)
	v_sub_f32_e32 v129, v129, v214
	v_sub_f32_e32 v128, v128, v214
	v_sub_f32_e32 v127, v127, v214
	v_sub_f32_e32 v126, v126, v214
	v_pk_mul_f32 v[126:127], v[214:215], v[126:127] op_sel:[1,0]
	v_pk_mul_f32 v[128:129], v[214:215], v[128:129] op_sel:[1,0]
	v_pk_fma_f32 v[126:127], v[134:135], v[126:127], v[138:139]
	v_pk_fma_f32 v[128:129], v[136:137], v[128:129], v[140:141]
	v_pk_mul_f32 v[128:129], v[128:129], s[88:89] op_sel_hi:[1,0]
	v_pk_mul_f32 v[126:127], v[126:127], s[88:89] op_sel_hi:[1,0]
	v_pk_fma_f32 v[96:97], v[96:97], v[132:133], v[128:129]
	v_pk_fma_f32 v[94:95], v[94:95], v[130:131], v[126:127]
	global_store_dwordx4 v196, v[94:97], s[10:11] offset:64
	s_nop 1
	global_load_dwordx4 v[94:97], v196, s[38:39] offset:512
	v_sub_f32_e32 v125, v125, v216
	v_sub_f32_e32 v124, v124, v216
	v_sub_f32_e32 v123, v123, v216
	v_sub_f32_e32 v122, v122, v216
	v_pk_mul_f32 v[122:123], v[216:217], v[122:123] op_sel:[1,0]
	v_pk_mul_f32 v[124:125], v[216:217], v[124:125] op_sel:[1,0]
	v_pk_fma_f32 v[122:123], v[134:135], v[122:123], v[138:139]
	v_pk_fma_f32 v[124:125], v[136:137], v[124:125], v[140:141]
	v_pk_mul_f32 v[124:125], v[124:125], s[88:89] op_sel_hi:[1,0]
	v_pk_mul_f32 v[122:123], v[122:123], s[88:89] op_sel_hi:[1,0]
	v_pk_fma_f32 v[92:93], v[92:93], v[132:133], v[124:125]
	v_pk_fma_f32 v[90:91], v[90:91], v[130:131], v[122:123]
	global_store_dwordx4 v197, v[90:93], s[10:11] offset:64
	s_nop 1
	global_load_dwordx4 v[90:93], v197, s[38:39] offset:512
	v_sub_f32_e32 v121, v121, v218
	v_sub_f32_e32 v120, v120, v218
	v_sub_f32_e32 v119, v119, v218
	v_sub_f32_e32 v118, v118, v218
	v_pk_mul_f32 v[118:119], v[218:219], v[118:119] op_sel:[1,0]
	v_pk_mul_f32 v[120:121], v[218:219], v[120:121] op_sel:[1,0]
	v_pk_fma_f32 v[118:119], v[134:135], v[118:119], v[138:139]
	v_pk_fma_f32 v[120:121], v[136:137], v[120:121], v[140:141]
	v_pk_mul_f32 v[120:121], v[120:121], s[88:89] op_sel_hi:[1,0]
	v_pk_mul_f32 v[118:119], v[118:119], s[88:89] op_sel_hi:[1,0]
	v_pk_fma_f32 v[88:89], v[88:89], v[132:133], v[120:121]
	v_pk_fma_f32 v[86:87], v[86:87], v[130:131], v[118:119]
	global_store_dwordx4 v198, v[86:89], s[10:11] offset:64
	s_nop 1
	global_load_dwordx4 v[86:89], v198, s[38:39] offset:512
	v_sub_f32_e32 v117, v117, v220
	v_sub_f32_e32 v116, v116, v220
	v_sub_f32_e32 v115, v115, v220
	v_sub_f32_e32 v114, v114, v220
	v_pk_mul_f32 v[114:115], v[220:221], v[114:115] op_sel:[1,0]
	v_pk_mul_f32 v[116:117], v[220:221], v[116:117] op_sel:[1,0]
	v_pk_fma_f32 v[114:115], v[134:135], v[114:115], v[138:139]
	v_pk_fma_f32 v[116:117], v[136:137], v[116:117], v[140:141]
	v_pk_mul_f32 v[116:117], v[116:117], s[88:89] op_sel_hi:[1,0]
	v_pk_mul_f32 v[114:115], v[114:115], s[88:89] op_sel_hi:[1,0]
	v_pk_fma_f32 v[84:85], v[84:85], v[132:133], v[116:117]
	v_pk_fma_f32 v[82:83], v[82:83], v[130:131], v[114:115]
	global_store_dwordx4 v199, v[82:85], s[10:11] offset:64
	s_nop 1
	global_load_dwordx4 v[82:85], v199, s[38:39] offset:512
	v_sub_f32_e32 v113, v113, v222
	v_sub_f32_e32 v112, v112, v222
	v_sub_f32_e32 v111, v111, v222
	v_sub_f32_e32 v110, v110, v222
	v_pk_mul_f32 v[110:111], v[222:223], v[110:111] op_sel:[1,0]
	v_pk_mul_f32 v[112:113], v[222:223], v[112:113] op_sel:[1,0]
	v_pk_fma_f32 v[110:111], v[134:135], v[110:111], v[138:139]
	v_pk_fma_f32 v[112:113], v[136:137], v[112:113], v[140:141]
	v_pk_mul_f32 v[112:113], v[112:113], s[88:89] op_sel_hi:[1,0]
	v_pk_mul_f32 v[110:111], v[110:111], s[88:89] op_sel_hi:[1,0]
	v_pk_fma_f32 v[80:81], v[80:81], v[132:133], v[112:113]
	v_pk_fma_f32 v[78:79], v[78:79], v[130:131], v[110:111]
	global_store_dwordx4 v200, v[78:81], s[10:11] offset:64
	s_nop 1
	global_load_dwordx4 v[78:81], v200, s[38:39] offset:512
	v_sub_f32_e32 v109, v109, v224
	v_sub_f32_e32 v108, v108, v224
	v_sub_f32_e32 v107, v107, v224
	v_sub_f32_e32 v106, v106, v224
	v_pk_mul_f32 v[106:107], v[224:225], v[106:107] op_sel:[1,0]
	v_pk_mul_f32 v[108:109], v[224:225], v[108:109] op_sel:[1,0]
	v_pk_fma_f32 v[106:107], v[134:135], v[106:107], v[138:139]
	v_pk_fma_f32 v[108:109], v[136:137], v[108:109], v[140:141]
	v_pk_mul_f32 v[108:109], v[108:109], s[88:89] op_sel_hi:[1,0]
	v_pk_mul_f32 v[106:107], v[106:107], s[88:89] op_sel_hi:[1,0]
	v_pk_fma_f32 v[76:77], v[76:77], v[132:133], v[108:109]
	v_pk_fma_f32 v[74:75], v[74:75], v[130:131], v[106:107]
	global_store_dwordx4 v201, v[74:77], s[10:11] offset:64
	s_nop 1
	global_load_dwordx4 v[74:77], v201, s[38:39] offset:512
	v_sub_f32_e32 v105, v105, v226
	v_sub_f32_e32 v104, v104, v226
	v_sub_f32_e32 v103, v103, v226
	v_sub_f32_e32 v102, v102, v226
	v_pk_mul_f32 v[102:103], v[226:227], v[102:103] op_sel:[1,0]
	v_pk_mul_f32 v[104:105], v[226:227], v[104:105] op_sel:[1,0]
	v_pk_fma_f32 v[102:103], v[134:135], v[102:103], v[138:139]
	v_pk_fma_f32 v[104:105], v[136:137], v[104:105], v[140:141]
	v_pk_mul_f32 v[104:105], v[104:105], s[88:89] op_sel_hi:[1,0]
	v_pk_mul_f32 v[102:103], v[102:103], s[88:89] op_sel_hi:[1,0]
	v_pk_fma_f32 v[72:73], v[72:73], v[132:133], v[104:105]
	v_pk_fma_f32 v[70:71], v[70:71], v[130:131], v[102:103]
	global_store_dwordx4 v202, v[70:73], s[10:11] offset:64
	s_nop 1
	global_load_dwordx4 v[70:73], v202, s[38:39] offset:512
	v_sub_f32_e32 v101, v101, v228
	v_sub_f32_e32 v100, v100, v228
	v_sub_f32_e32 v99, v99, v228
	v_sub_f32_e32 v98, v98, v228
	v_pk_mul_f32 v[98:99], v[228:229], v[98:99] op_sel:[1,0]
	v_pk_mul_f32 v[100:101], v[228:229], v[100:101] op_sel:[1,0]
	v_pk_fma_f32 v[98:99], v[134:135], v[98:99], v[138:139]
	v_pk_fma_f32 v[100:101], v[136:137], v[100:101], v[140:141]
	v_pk_mul_f32 v[100:101], v[100:101], s[88:89] op_sel_hi:[1,0]
	v_pk_mul_f32 v[98:99], v[98:99], s[88:89] op_sel_hi:[1,0]
	v_pk_fma_f32 v[68:69], v[68:69], v[132:133], v[100:101]
	v_pk_fma_f32 v[66:67], v[66:67], v[130:131], v[98:99]
	global_store_dwordx4 v203, v[66:69], s[10:11] offset:64
	s_nop 1
	global_load_dwordx4 v[66:69], v203, s[38:39] offset:512
	global_load_dwordx4 v[130:133], v[236:237], off offset:512
	global_load_dwordx4 v[134:137], v234, s[18:19] offset:512
	global_load_dwordx4 v[138:141], v234, s[6:7] offset:512
	s_waitcnt vmcnt(0)
	v_sub_f32_e32 v97, v97, v214
	v_sub_f32_e32 v96, v96, v214
	v_sub_f32_e32 v95, v95, v214
	v_sub_f32_e32 v94, v94, v214
	v_pk_mul_f32 v[94:95], v[214:215], v[94:95] op_sel:[1,0]
	v_pk_mul_f32 v[96:97], v[214:215], v[96:97] op_sel:[1,0]
	v_pk_fma_f32 v[94:95], v[134:135], v[94:95], v[138:139]
	v_pk_fma_f32 v[96:97], v[136:137], v[96:97], v[140:141]
	v_pk_mul_f32 v[96:97], v[96:97], s[88:89] op_sel_hi:[1,0]
	v_pk_mul_f32 v[94:95], v[94:95], s[88:89] op_sel_hi:[1,0]
	v_pk_fma_f32 v[64:65], v[64:65], v[132:133], v[96:97]
	v_pk_fma_f32 v[62:63], v[62:63], v[130:131], v[94:95]
	global_store_dwordx4 v196, v[62:65], s[10:11] offset:512
	s_nop 1
	global_load_dwordx4 v[62:65], v196, s[38:39] offset:576
	v_sub_f32_e32 v93, v93, v216
	v_sub_f32_e32 v92, v92, v216
	v_sub_f32_e32 v91, v91, v216
	v_sub_f32_e32 v90, v90, v216
	v_pk_mul_f32 v[90:91], v[216:217], v[90:91] op_sel:[1,0]
	v_pk_mul_f32 v[92:93], v[216:217], v[92:93] op_sel:[1,0]
	v_pk_fma_f32 v[90:91], v[134:135], v[90:91], v[138:139]
	v_pk_fma_f32 v[92:93], v[136:137], v[92:93], v[140:141]
	v_pk_mul_f32 v[92:93], v[92:93], s[88:89] op_sel_hi:[1,0]
	v_pk_mul_f32 v[90:91], v[90:91], s[88:89] op_sel_hi:[1,0]
	v_pk_fma_f32 v[60:61], v[60:61], v[132:133], v[92:93]
	v_pk_fma_f32 v[58:59], v[58:59], v[130:131], v[90:91]
	global_store_dwordx4 v197, v[58:61], s[10:11] offset:512
	s_nop 1
	global_load_dwordx4 v[58:61], v197, s[38:39] offset:576
	v_sub_f32_e32 v89, v89, v218
	v_sub_f32_e32 v88, v88, v218
	v_sub_f32_e32 v87, v87, v218
	v_sub_f32_e32 v86, v86, v218
	v_pk_mul_f32 v[86:87], v[218:219], v[86:87] op_sel:[1,0]
	v_pk_mul_f32 v[88:89], v[218:219], v[88:89] op_sel:[1,0]
	v_pk_fma_f32 v[86:87], v[134:135], v[86:87], v[138:139]
	v_pk_fma_f32 v[88:89], v[136:137], v[88:89], v[140:141]
	v_pk_mul_f32 v[88:89], v[88:89], s[88:89] op_sel_hi:[1,0]
	v_pk_mul_f32 v[86:87], v[86:87], s[88:89] op_sel_hi:[1,0]
	v_pk_fma_f32 v[56:57], v[56:57], v[132:133], v[88:89]
	v_pk_fma_f32 v[54:55], v[54:55], v[130:131], v[86:87]
	global_store_dwordx4 v198, v[54:57], s[10:11] offset:512
	s_nop 1
	global_load_dwordx4 v[54:57], v198, s[38:39] offset:576
	v_sub_f32_e32 v85, v85, v220
	v_sub_f32_e32 v84, v84, v220
	v_sub_f32_e32 v83, v83, v220
	v_sub_f32_e32 v82, v82, v220
	v_pk_mul_f32 v[82:83], v[220:221], v[82:83] op_sel:[1,0]
	v_pk_mul_f32 v[84:85], v[220:221], v[84:85] op_sel:[1,0]
	v_pk_fma_f32 v[82:83], v[134:135], v[82:83], v[138:139]
	v_pk_fma_f32 v[84:85], v[136:137], v[84:85], v[140:141]
	v_pk_mul_f32 v[84:85], v[84:85], s[88:89] op_sel_hi:[1,0]
	v_pk_mul_f32 v[82:83], v[82:83], s[88:89] op_sel_hi:[1,0]
	v_pk_fma_f32 v[52:53], v[52:53], v[132:133], v[84:85]
	v_pk_fma_f32 v[50:51], v[50:51], v[130:131], v[82:83]
	global_store_dwordx4 v199, v[50:53], s[10:11] offset:512
	s_nop 1
	global_load_dwordx4 v[50:53], v199, s[38:39] offset:576
	v_sub_f32_e32 v81, v81, v222
	v_sub_f32_e32 v80, v80, v222
	v_sub_f32_e32 v79, v79, v222
	v_sub_f32_e32 v78, v78, v222
	v_pk_mul_f32 v[78:79], v[222:223], v[78:79] op_sel:[1,0]
	v_pk_mul_f32 v[80:81], v[222:223], v[80:81] op_sel:[1,0]
	v_pk_fma_f32 v[78:79], v[134:135], v[78:79], v[138:139]
	v_pk_fma_f32 v[80:81], v[136:137], v[80:81], v[140:141]
	v_pk_mul_f32 v[80:81], v[80:81], s[88:89] op_sel_hi:[1,0]
	v_pk_mul_f32 v[78:79], v[78:79], s[88:89] op_sel_hi:[1,0]
	v_pk_fma_f32 v[48:49], v[48:49], v[132:133], v[80:81]
	v_pk_fma_f32 v[46:47], v[46:47], v[130:131], v[78:79]
	global_store_dwordx4 v200, v[46:49], s[10:11] offset:512
	s_nop 1
	global_load_dwordx4 v[46:49], v200, s[38:39] offset:576
	v_sub_f32_e32 v77, v77, v224
	v_sub_f32_e32 v76, v76, v224
	v_sub_f32_e32 v75, v75, v224
	v_sub_f32_e32 v74, v74, v224
	v_pk_mul_f32 v[74:75], v[224:225], v[74:75] op_sel:[1,0]
	v_pk_mul_f32 v[76:77], v[224:225], v[76:77] op_sel:[1,0]
	v_pk_fma_f32 v[74:75], v[134:135], v[74:75], v[138:139]
	v_pk_fma_f32 v[76:77], v[136:137], v[76:77], v[140:141]
	v_pk_mul_f32 v[76:77], v[76:77], s[88:89] op_sel_hi:[1,0]
	v_pk_mul_f32 v[74:75], v[74:75], s[88:89] op_sel_hi:[1,0]
	v_pk_fma_f32 v[44:45], v[44:45], v[132:133], v[76:77]
	v_pk_fma_f32 v[42:43], v[42:43], v[130:131], v[74:75]
	global_store_dwordx4 v201, v[42:45], s[10:11] offset:512
	s_nop 1
	global_load_dwordx4 v[42:45], v201, s[38:39] offset:576
	v_sub_f32_e32 v73, v73, v226
	v_sub_f32_e32 v72, v72, v226
	v_sub_f32_e32 v71, v71, v226
	v_sub_f32_e32 v70, v70, v226
	v_pk_mul_f32 v[70:71], v[226:227], v[70:71] op_sel:[1,0]
	v_pk_mul_f32 v[72:73], v[226:227], v[72:73] op_sel:[1,0]
	v_pk_fma_f32 v[70:71], v[134:135], v[70:71], v[138:139]
	v_pk_fma_f32 v[72:73], v[136:137], v[72:73], v[140:141]
	v_pk_mul_f32 v[72:73], v[72:73], s[88:89] op_sel_hi:[1,0]
	v_pk_mul_f32 v[70:71], v[70:71], s[88:89] op_sel_hi:[1,0]
	v_pk_fma_f32 v[40:41], v[40:41], v[132:133], v[72:73]
	v_pk_fma_f32 v[38:39], v[38:39], v[130:131], v[70:71]
	global_store_dwordx4 v202, v[38:41], s[10:11] offset:512
	s_nop 1
	global_load_dwordx4 v[38:41], v202, s[38:39] offset:576
	v_sub_f32_e32 v69, v69, v228
	v_sub_f32_e32 v68, v68, v228
	v_sub_f32_e32 v67, v67, v228
	v_sub_f32_e32 v66, v66, v228
	v_pk_mul_f32 v[66:67], v[228:229], v[66:67] op_sel:[1,0]
	v_pk_mul_f32 v[68:69], v[228:229], v[68:69] op_sel:[1,0]
	v_pk_fma_f32 v[66:67], v[134:135], v[66:67], v[138:139]
	v_pk_fma_f32 v[68:69], v[136:137], v[68:69], v[140:141]
	v_pk_mul_f32 v[68:69], v[68:69], s[88:89] op_sel_hi:[1,0]
	v_pk_mul_f32 v[66:67], v[66:67], s[88:89] op_sel_hi:[1,0]
	v_pk_fma_f32 v[36:37], v[36:37], v[132:133], v[68:69]
	v_pk_fma_f32 v[34:35], v[34:35], v[130:131], v[66:67]
	global_store_dwordx4 v203, v[34:37], s[10:11] offset:512
	s_nop 1
	global_load_dwordx4 v[34:37], v203, s[38:39] offset:576
	global_load_dwordx4 v[130:133], v[236:237], off offset:576
	global_load_dwordx4 v[134:137], v234, s[18:19] offset:576
	global_load_dwordx4 v[138:141], v234, s[6:7] offset:576
	s_waitcnt vmcnt(0)
	v_sub_f32_e32 v65, v65, v214
	v_sub_f32_e32 v64, v64, v214
	v_sub_f32_e32 v63, v63, v214
	v_sub_f32_e32 v62, v62, v214
	v_pk_mul_f32 v[62:63], v[214:215], v[62:63] op_sel:[1,0]
	v_pk_mul_f32 v[64:65], v[214:215], v[64:65] op_sel:[1,0]
	v_pk_fma_f32 v[62:63], v[134:135], v[62:63], v[138:139]
	v_pk_fma_f32 v[64:65], v[136:137], v[64:65], v[140:141]
	v_pk_mul_f32 v[64:65], v[64:65], s[88:89] op_sel_hi:[1,0]
	v_pk_mul_f32 v[62:63], v[62:63], s[88:89] op_sel_hi:[1,0]
	v_pk_fma_f32 v[32:33], v[32:33], v[132:133], v[64:65]
	v_pk_fma_f32 v[30:31], v[30:31], v[130:131], v[62:63]
	global_store_dwordx4 v196, v[30:33], s[10:11] offset:576
	v_sub_f32_e32 v61, v61, v216
	v_sub_f32_e32 v60, v60, v216
	v_sub_f32_e32 v59, v59, v216
	v_sub_f32_e32 v58, v58, v216
	v_pk_mul_f32 v[58:59], v[216:217], v[58:59] op_sel:[1,0]
	v_pk_mul_f32 v[60:61], v[216:217], v[60:61] op_sel:[1,0]
	v_pk_fma_f32 v[58:59], v[134:135], v[58:59], v[138:139]
	v_pk_fma_f32 v[60:61], v[136:137], v[60:61], v[140:141]
	v_pk_mul_f32 v[60:61], v[60:61], s[88:89] op_sel_hi:[1,0]
	v_pk_mul_f32 v[58:59], v[58:59], s[88:89] op_sel_hi:[1,0]
	v_pk_fma_f32 v[28:29], v[28:29], v[132:133], v[60:61]
	v_pk_fma_f32 v[26:27], v[26:27], v[130:131], v[58:59]
	global_store_dwordx4 v197, v[26:29], s[10:11] offset:576
	v_sub_f32_e32 v57, v57, v218
	v_sub_f32_e32 v56, v56, v218
	v_sub_f32_e32 v55, v55, v218
	v_sub_f32_e32 v54, v54, v218
	v_pk_mul_f32 v[54:55], v[218:219], v[54:55] op_sel:[1,0]
	v_pk_mul_f32 v[56:57], v[218:219], v[56:57] op_sel:[1,0]
	v_pk_fma_f32 v[54:55], v[134:135], v[54:55], v[138:139]
	v_pk_fma_f32 v[56:57], v[136:137], v[56:57], v[140:141]
	v_pk_mul_f32 v[56:57], v[56:57], s[88:89] op_sel_hi:[1,0]
	v_pk_mul_f32 v[54:55], v[54:55], s[88:89] op_sel_hi:[1,0]
	v_pk_fma_f32 v[24:25], v[24:25], v[132:133], v[56:57]
	v_pk_fma_f32 v[22:23], v[22:23], v[130:131], v[54:55]
	global_store_dwordx4 v198, v[22:25], s[10:11] offset:576
	v_sub_f32_e32 v53, v53, v220
	v_sub_f32_e32 v52, v52, v220
	v_sub_f32_e32 v51, v51, v220
	v_sub_f32_e32 v50, v50, v220
	v_pk_mul_f32 v[50:51], v[220:221], v[50:51] op_sel:[1,0]
	v_pk_mul_f32 v[52:53], v[220:221], v[52:53] op_sel:[1,0]
	v_pk_fma_f32 v[50:51], v[134:135], v[50:51], v[138:139]
	v_pk_fma_f32 v[52:53], v[136:137], v[52:53], v[140:141]
	v_pk_mul_f32 v[52:53], v[52:53], s[88:89] op_sel_hi:[1,0]
	v_pk_mul_f32 v[50:51], v[50:51], s[88:89] op_sel_hi:[1,0]
	v_pk_fma_f32 v[20:21], v[20:21], v[132:133], v[52:53]
	v_pk_fma_f32 v[18:19], v[18:19], v[130:131], v[50:51]
	global_store_dwordx4 v199, v[18:21], s[10:11] offset:576
	v_sub_f32_e32 v49, v49, v222
	v_sub_f32_e32 v48, v48, v222
	v_sub_f32_e32 v47, v47, v222
	v_sub_f32_e32 v46, v46, v222
	v_pk_mul_f32 v[46:47], v[222:223], v[46:47] op_sel:[1,0]
	v_pk_mul_f32 v[48:49], v[222:223], v[48:49] op_sel:[1,0]
	v_pk_fma_f32 v[46:47], v[134:135], v[46:47], v[138:139]
	v_pk_fma_f32 v[48:49], v[136:137], v[48:49], v[140:141]
	v_pk_mul_f32 v[48:49], v[48:49], s[88:89] op_sel_hi:[1,0]
	v_pk_mul_f32 v[46:47], v[46:47], s[88:89] op_sel_hi:[1,0]
	v_pk_fma_f32 v[16:17], v[16:17], v[132:133], v[48:49]
	v_pk_fma_f32 v[14:15], v[14:15], v[130:131], v[46:47]
	global_store_dwordx4 v200, v[14:17], s[10:11] offset:576
	v_sub_f32_e32 v45, v45, v224
	v_sub_f32_e32 v44, v44, v224
	v_sub_f32_e32 v43, v43, v224
	v_sub_f32_e32 v42, v42, v224
	v_pk_mul_f32 v[42:43], v[224:225], v[42:43] op_sel:[1,0]
	v_pk_mul_f32 v[44:45], v[224:225], v[44:45] op_sel:[1,0]
	v_pk_fma_f32 v[42:43], v[134:135], v[42:43], v[138:139]
	v_pk_fma_f32 v[44:45], v[136:137], v[44:45], v[140:141]
	v_pk_mul_f32 v[44:45], v[44:45], s[88:89] op_sel_hi:[1,0]
	v_pk_mul_f32 v[42:43], v[42:43], s[88:89] op_sel_hi:[1,0]
	v_pk_fma_f32 v[12:13], v[12:13], v[132:133], v[44:45]
	v_pk_fma_f32 v[10:11], v[10:11], v[130:131], v[42:43]
	global_store_dwordx4 v201, v[10:13], s[10:11] offset:576
	v_sub_f32_e32 v41, v41, v226
	v_sub_f32_e32 v40, v40, v226
	v_sub_f32_e32 v39, v39, v226
	v_sub_f32_e32 v38, v38, v226
	v_pk_mul_f32 v[38:39], v[226:227], v[38:39] op_sel:[1,0]
	v_pk_mul_f32 v[40:41], v[226:227], v[40:41] op_sel:[1,0]
	v_pk_fma_f32 v[38:39], v[134:135], v[38:39], v[138:139]
	v_pk_fma_f32 v[40:41], v[136:137], v[40:41], v[140:141]
	v_pk_mul_f32 v[40:41], v[40:41], s[88:89] op_sel_hi:[1,0]
	v_pk_mul_f32 v[38:39], v[38:39], s[88:89] op_sel_hi:[1,0]
	v_pk_fma_f32 v[8:9], v[8:9], v[132:133], v[40:41]
	v_pk_fma_f32 v[6:7], v[6:7], v[130:131], v[38:39]
	global_store_dwordx4 v202, v[6:9], s[10:11] offset:576
	v_sub_f32_e32 v37, v37, v228
	v_sub_f32_e32 v36, v36, v228
	v_sub_f32_e32 v35, v35, v228
	v_sub_f32_e32 v34, v34, v228
	v_pk_mul_f32 v[34:35], v[228:229], v[34:35] op_sel:[1,0]
	v_pk_mul_f32 v[36:37], v[228:229], v[36:37] op_sel:[1,0]
	v_pk_fma_f32 v[34:35], v[134:135], v[34:35], v[138:139]
	v_pk_fma_f32 v[36:37], v[136:137], v[36:37], v[140:141]
	v_pk_mul_f32 v[36:37], v[36:37], s[88:89] op_sel_hi:[1,0]
	v_pk_mul_f32 v[34:35], v[34:35], s[88:89] op_sel_hi:[1,0]
	v_pk_fma_f32 v[4:5], v[4:5], v[132:133], v[36:37]
	v_pk_fma_f32 v[2:3], v[2:3], v[130:131], v[34:35]
	global_store_dwordx4 v203, v[2:5], s[10:11] offset:576
	s_branch .Lp6epi_done
.Lp6epi_nostats:
	global_load_dwordx4 v[130:133], v[236:237], off
	global_load_dwordx4 v[164:167], v196, s[38:39]
	global_load_dwordx4 v[168:171], v197, s[38:39]
	global_load_dwordx4 v[172:175], v198, s[38:39]
	global_load_dwordx4 v[176:179], v199, s[38:39]
	global_load_dwordx4 v[184:187], v200, s[38:39]
	global_load_dwordx4 v[188:191], v201, s[38:39]
	global_load_dwordx4 v[192:195], v202, s[38:39]
	global_load_dwordx4 v[230:233], v203, s[38:39]
	s_waitcnt vmcnt(0)
	v_pk_mul_f32 v[166:167], v[166:167], s[88:89] op_sel_hi:[1,0]
	v_pk_mul_f32 v[164:165], v[164:165], s[88:89] op_sel_hi:[1,0]
	v_pk_fma_f32 v[128:129], v[128:129], v[132:133], v[166:167]
	v_pk_fma_f32 v[126:127], v[126:127], v[130:131], v[164:165]
	global_store_dwordx4 v196, v[126:129], s[10:11]
	s_nop 1
	global_load_dwordx4 v[126:129], v196, s[38:39] offset:64
	v_pk_mul_f32 v[170:171], v[170:171], s[88:89] op_sel_hi:[1,0]
	v_pk_mul_f32 v[168:169], v[168:169], s[88:89] op_sel_hi:[1,0]
	v_pk_fma_f32 v[124:125], v[124:125], v[132:133], v[170:171]
	v_pk_fma_f32 v[122:123], v[122:123], v[130:131], v[168:169]
	global_store_dwordx4 v197, v[122:125], s[10:11]
	s_nop 1
	global_load_dwordx4 v[122:125], v197, s[38:39] offset:64
	v_pk_mul_f32 v[174:175], v[174:175], s[88:89] op_sel_hi:[1,0]
	v_pk_mul_f32 v[172:173], v[172:173], s[88:89] op_sel_hi:[1,0]
	v_pk_fma_f32 v[120:121], v[120:121], v[132:133], v[174:175]
	v_pk_fma_f32 v[118:119], v[118:119], v[130:131], v[172:173]
	global_store_dwordx4 v198, v[118:121], s[10:11]
	s_nop 1
	global_load_dwordx4 v[118:121], v198, s[38:39] offset:64
	v_pk_mul_f32 v[178:179], v[178:179], s[88:89] op_sel_hi:[1,0]
	v_pk_mul_f32 v[176:177], v[176:177], s[88:89] op_sel_hi:[1,0]
	v_pk_fma_f32 v[116:117], v[116:117], v[132:133], v[178:179]
	v_pk_fma_f32 v[114:115], v[114:115], v[130:131], v[176:177]
	global_store_dwordx4 v199, v[114:117], s[10:11]
	s_nop 1
	global_load_dwordx4 v[114:117], v199, s[38:39] offset:64
	v_pk_mul_f32 v[186:187], v[186:187], s[88:89] op_sel_hi:[1,0]
	v_pk_mul_f32 v[184:185], v[184:185], s[88:89] op_sel_hi:[1,0]
	v_pk_fma_f32 v[112:113], v[112:113], v[132:133], v[186:187]
	v_pk_fma_f32 v[110:111], v[110:111], v[130:131], v[184:185]
	global_store_dwordx4 v200, v[110:113], s[10:11]
	s_nop 1
	global_load_dwordx4 v[110:113], v200, s[38:39] offset:64
	v_pk_mul_f32 v[190:191], v[190:191], s[88:89] op_sel_hi:[1,0]
	v_pk_mul_f32 v[188:189], v[188:189], s[88:89] op_sel_hi:[1,0]
	v_pk_fma_f32 v[108:109], v[108:109], v[132:133], v[190:191]
	v_pk_fma_f32 v[106:107], v[106:107], v[130:131], v[188:189]
	global_store_dwordx4 v201, v[106:109], s[10:11]
	s_nop 1
	global_load_dwordx4 v[106:109], v201, s[38:39] offset:64
	v_pk_mul_f32 v[194:195], v[194:195], s[88:89] op_sel_hi:[1,0]
	v_pk_mul_f32 v[192:193], v[192:193], s[88:89] op_sel_hi:[1,0]
	v_pk_fma_f32 v[104:105], v[104:105], v[132:133], v[194:195]
	v_pk_fma_f32 v[102:103], v[102:103], v[130:131], v[192:193]
	global_store_dwordx4 v202, v[102:105], s[10:11]
	s_nop 1
	global_load_dwordx4 v[102:105], v202, s[38:39] offset:64
	v_pk_mul_f32 v[232:233], v[232:233], s[88:89] op_sel_hi:[1,0]
	v_pk_mul_f32 v[230:231], v[230:231], s[88:89] op_sel_hi:[1,0]
	v_pk_fma_f32 v[100:101], v[100:101], v[132:133], v[232:233]
	v_pk_fma_f32 v[98:99], v[98:99], v[130:131], v[230:231]
	global_store_dwordx4 v203, v[98:101], s[10:11]
	s_nop 1
	global_load_dwordx4 v[98:101], v203, s[38:39] offset:64
	global_load_dwordx4 v[130:133], v[236:237], off offset:64
	s_waitcnt vmcnt(0)
	v_pk_mul_f32 v[128:129], v[128:129], s[88:89] op_sel_hi:[1,0]
	v_pk_mul_f32 v[126:127], v[126:127], s[88:89] op_sel_hi:[1,0]
	v_pk_fma_f32 v[96:97], v[96:97], v[132:133], v[128:129]
	v_pk_fma_f32 v[94:95], v[94:95], v[130:131], v[126:127]
	global_store_dwordx4 v196, v[94:97], s[10:11] offset:64
	s_nop 1
	global_load_dwordx4 v[94:97], v196, s[38:39] offset:512
	v_pk_mul_f32 v[124:125], v[124:125], s[88:89] op_sel_hi:[1,0]
	v_pk_mul_f32 v[122:123], v[122:123], s[88:89] op_sel_hi:[1,0]
	v_pk_fma_f32 v[92:93], v[92:93], v[132:133], v[124:125]
	v_pk_fma_f32 v[90:91], v[90:91], v[130:131], v[122:123]
	global_store_dwordx4 v197, v[90:93], s[10:11] offset:64
	s_nop 1
	global_load_dwordx4 v[90:93], v197, s[38:39] offset:512
	v_pk_mul_f32 v[120:121], v[120:121], s[88:89] op_sel_hi:[1,0]
	v_pk_mul_f32 v[118:119], v[118:119], s[88:89] op_sel_hi:[1,0]
	v_pk_fma_f32 v[88:89], v[88:89], v[132:133], v[120:121]
	v_pk_fma_f32 v[86:87], v[86:87], v[130:131], v[118:119]
	global_store_dwordx4 v198, v[86:89], s[10:11] offset:64
	s_nop 1
	global_load_dwordx4 v[86:89], v198, s[38:39] offset:512
	v_pk_mul_f32 v[116:117], v[116:117], s[88:89] op_sel_hi:[1,0]
	v_pk_mul_f32 v[114:115], v[114:115], s[88:89] op_sel_hi:[1,0]
	v_pk_fma_f32 v[84:85], v[84:85], v[132:133], v[116:117]
	v_pk_fma_f32 v[82:83], v[82:83], v[130:131], v[114:115]
	global_store_dwordx4 v199, v[82:85], s[10:11] offset:64
	s_nop 1
	global_load_dwordx4 v[82:85], v199, s[38:39] offset:512
	v_pk_mul_f32 v[112:113], v[112:113], s[88:89] op_sel_hi:[1,0]
	v_pk_mul_f32 v[110:111], v[110:111], s[88:89] op_sel_hi:[1,0]
	v_pk_fma_f32 v[80:81], v[80:81], v[132:133], v[112:113]
	v_pk_fma_f32 v[78:79], v[78:79], v[130:131], v[110:111]
	global_store_dwordx4 v200, v[78:81], s[10:11] offset:64
	s_nop 1
	global_load_dwordx4 v[78:81], v200, s[38:39] offset:512
	v_pk_mul_f32 v[108:109], v[108:109], s[88:89] op_sel_hi:[1,0]
	v_pk_mul_f32 v[106:107], v[106:107], s[88:89] op_sel_hi:[1,0]
	v_pk_fma_f32 v[76:77], v[76:77], v[132:133], v[108:109]
	v_pk_fma_f32 v[74:75], v[74:75], v[130:131], v[106:107]
	global_store_dwordx4 v201, v[74:77], s[10:11] offset:64
	s_nop 1
	global_load_dwordx4 v[74:77], v201, s[38:39] offset:512
	v_pk_mul_f32 v[104:105], v[104:105], s[88:89] op_sel_hi:[1,0]
	v_pk_mul_f32 v[102:103], v[102:103], s[88:89] op_sel_hi:[1,0]
	v_pk_fma_f32 v[72:73], v[72:73], v[132:133], v[104:105]
	v_pk_fma_f32 v[70:71], v[70:71], v[130:131], v[102:103]
	global_store_dwordx4 v202, v[70:73], s[10:11] offset:64
	s_nop 1
	global_load_dwordx4 v[70:73], v202, s[38:39] offset:512
	v_pk_mul_f32 v[100:101], v[100:101], s[88:89] op_sel_hi:[1,0]
	v_pk_mul_f32 v[98:99], v[98:99], s[88:89] op_sel_hi:[1,0]
	v_pk_fma_f32 v[68:69], v[68:69], v[132:133], v[100:101]
	v_pk_fma_f32 v[66:67], v[66:67], v[130:131], v[98:99]
	global_store_dwordx4 v203, v[66:69], s[10:11] offset:64
	s_nop 1
	global_load_dwordx4 v[66:69], v203, s[38:39] offset:512
	global_load_dwordx4 v[130:133], v[236:237], off offset:512
	s_waitcnt vmcnt(0)
	v_pk_mul_f32 v[96:97], v[96:97], s[88:89] op_sel_hi:[1,0]
	v_pk_mul_f32 v[94:95], v[94:95], s[88:89] op_sel_hi:[1,0]
	v_pk_fma_f32 v[64:65], v[64:65], v[132:133], v[96:97]
	v_pk_fma_f32 v[62:63], v[62:63], v[130:131], v[94:95]
	global_store_dwordx4 v196, v[62:65], s[10:11] offset:512
	s_nop 1
	global_load_dwordx4 v[62:65], v196, s[38:39] offset:576
	v_pk_mul_f32 v[92:93], v[92:93], s[88:89] op_sel_hi:[1,0]
	v_pk_mul_f32 v[90:91], v[90:91], s[88:89] op_sel_hi:[1,0]
	v_pk_fma_f32 v[60:61], v[60:61], v[132:133], v[92:93]
	v_pk_fma_f32 v[58:59], v[58:59], v[130:131], v[90:91]
	global_store_dwordx4 v197, v[58:61], s[10:11] offset:512
	s_nop 1
	global_load_dwordx4 v[58:61], v197, s[38:39] offset:576
	v_pk_mul_f32 v[88:89], v[88:89], s[88:89] op_sel_hi:[1,0]
	v_pk_mul_f32 v[86:87], v[86:87], s[88:89] op_sel_hi:[1,0]
	v_pk_fma_f32 v[56:57], v[56:57], v[132:133], v[88:89]
	v_pk_fma_f32 v[54:55], v[54:55], v[130:131], v[86:87]
	global_store_dwordx4 v198, v[54:57], s[10:11] offset:512
	s_nop 1
	global_load_dwordx4 v[54:57], v198, s[38:39] offset:576
	v_pk_mul_f32 v[84:85], v[84:85], s[88:89] op_sel_hi:[1,0]
	v_pk_mul_f32 v[82:83], v[82:83], s[88:89] op_sel_hi:[1,0]
	v_pk_fma_f32 v[52:53], v[52:53], v[132:133], v[84:85]
	v_pk_fma_f32 v[50:51], v[50:51], v[130:131], v[82:83]
	global_store_dwordx4 v199, v[50:53], s[10:11] offset:512
	s_nop 1
	global_load_dwordx4 v[50:53], v199, s[38:39] offset:576
	v_pk_mul_f32 v[80:81], v[80:81], s[88:89] op_sel_hi:[1,0]
	v_pk_mul_f32 v[78:79], v[78:79], s[88:89] op_sel_hi:[1,0]
	v_pk_fma_f32 v[48:49], v[48:49], v[132:133], v[80:81]
	v_pk_fma_f32 v[46:47], v[46:47], v[130:131], v[78:79]
	global_store_dwordx4 v200, v[46:49], s[10:11] offset:512
	s_nop 1
	global_load_dwordx4 v[46:49], v200, s[38:39] offset:576
	v_pk_mul_f32 v[76:77], v[76:77], s[88:89] op_sel_hi:[1,0]
	v_pk_mul_f32 v[74:75], v[74:75], s[88:89] op_sel_hi:[1,0]
	v_pk_fma_f32 v[44:45], v[44:45], v[132:133], v[76:77]
	v_pk_fma_f32 v[42:43], v[42:43], v[130:131], v[74:75]
	global_store_dwordx4 v201, v[42:45], s[10:11] offset:512
	s_nop 1
	global_load_dwordx4 v[42:45], v201, s[38:39] offset:576
	v_pk_mul_f32 v[72:73], v[72:73], s[88:89] op_sel_hi:[1,0]
	v_pk_mul_f32 v[70:71], v[70:71], s[88:89] op_sel_hi:[1,0]
	v_pk_fma_f32 v[40:41], v[40:41], v[132:133], v[72:73]
	v_pk_fma_f32 v[38:39], v[38:39], v[130:131], v[70:71]
	global_store_dwordx4 v202, v[38:41], s[10:11] offset:512
	s_nop 1
	global_load_dwordx4 v[38:41], v202, s[38:39] offset:576
	v_pk_mul_f32 v[68:69], v[68:69], s[88:89] op_sel_hi:[1,0]
	v_pk_mul_f32 v[66:67], v[66:67], s[88:89] op_sel_hi:[1,0]
	v_pk_fma_f32 v[36:37], v[36:37], v[132:133], v[68:69]
	v_pk_fma_f32 v[34:35], v[34:35], v[130:131], v[66:67]
	global_store_dwordx4 v203, v[34:37], s[10:11] offset:512
	s_nop 1
	global_load_dwordx4 v[34:37], v203, s[38:39] offset:576
	global_load_dwordx4 v[130:133], v[236:237], off offset:576
	s_waitcnt vmcnt(0)
	v_pk_mul_f32 v[64:65], v[64:65], s[88:89] op_sel_hi:[1,0]
	v_pk_mul_f32 v[62:63], v[62:63], s[88:89] op_sel_hi:[1,0]
	v_pk_fma_f32 v[32:33], v[32:33], v[132:133], v[64:65]
	v_pk_fma_f32 v[30:31], v[30:31], v[130:131], v[62:63]
	global_store_dwordx4 v196, v[30:33], s[10:11] offset:576
	v_pk_mul_f32 v[60:61], v[60:61], s[88:89] op_sel_hi:[1,0]
	v_pk_mul_f32 v[58:59], v[58:59], s[88:89] op_sel_hi:[1,0]
	v_pk_fma_f32 v[28:29], v[28:29], v[132:133], v[60:61]
	v_pk_fma_f32 v[26:27], v[26:27], v[130:131], v[58:59]
	global_store_dwordx4 v197, v[26:29], s[10:11] offset:576
	v_pk_mul_f32 v[56:57], v[56:57], s[88:89] op_sel_hi:[1,0]
	v_pk_mul_f32 v[54:55], v[54:55], s[88:89] op_sel_hi:[1,0]
	v_pk_fma_f32 v[24:25], v[24:25], v[132:133], v[56:57]
	v_pk_fma_f32 v[22:23], v[22:23], v[130:131], v[54:55]
	global_store_dwordx4 v198, v[22:25], s[10:11] offset:576
	v_pk_mul_f32 v[52:53], v[52:53], s[88:89] op_sel_hi:[1,0]
	v_pk_mul_f32 v[50:51], v[50:51], s[88:89] op_sel_hi:[1,0]
	v_pk_fma_f32 v[20:21], v[20:21], v[132:133], v[52:53]
	v_pk_fma_f32 v[18:19], v[18:19], v[130:131], v[50:51]
	global_store_dwordx4 v199, v[18:21], s[10:11] offset:576
	v_pk_mul_f32 v[48:49], v[48:49], s[88:89] op_sel_hi:[1,0]
	v_pk_mul_f32 v[46:47], v[46:47], s[88:89] op_sel_hi:[1,0]
	v_pk_fma_f32 v[16:17], v[16:17], v[132:133], v[48:49]
	v_pk_fma_f32 v[14:15], v[14:15], v[130:131], v[46:47]
	global_store_dwordx4 v200, v[14:17], s[10:11] offset:576
	v_pk_mul_f32 v[44:45], v[44:45], s[88:89] op_sel_hi:[1,0]
	v_pk_mul_f32 v[42:43], v[42:43], s[88:89] op_sel_hi:[1,0]
	v_pk_fma_f32 v[12:13], v[12:13], v[132:133], v[44:45]
	v_pk_fma_f32 v[10:11], v[10:11], v[130:131], v[42:43]
	global_store_dwordx4 v201, v[10:13], s[10:11] offset:576
	v_pk_mul_f32 v[40:41], v[40:41], s[88:89] op_sel_hi:[1,0]
	v_pk_mul_f32 v[38:39], v[38:39], s[88:89] op_sel_hi:[1,0]
	v_pk_fma_f32 v[8:9], v[8:9], v[132:133], v[40:41]
	v_pk_fma_f32 v[6:7], v[6:7], v[130:131], v[38:39]
	global_store_dwordx4 v202, v[6:9], s[10:11] offset:576
	v_pk_mul_f32 v[36:37], v[36:37], s[88:89] op_sel_hi:[1,0]
	v_pk_mul_f32 v[34:35], v[34:35], s[88:89] op_sel_hi:[1,0]
	v_pk_fma_f32 v[4:5], v[4:5], v[132:133], v[36:37]
	v_pk_fma_f32 v[2:3], v[2:3], v[130:131], v[34:35]
	global_store_dwordx4 v203, v[2:5], s[10:11] offset:576
	s_branch .Lp6epi_done
.Lp6epi_done:
	s_andn2_b64 vcc, exec, s[4:5]
	s_mov_b64 s[4:5], -1
	s_cbranch_vccnz .LBB0_1376
	s_andn2_b64 vcc, exec, s[20:21]
	s_cbranch_vccnz .LBB0_1375
	s_barrier
	s_branch .LBB0_1375

.LBB0_1816:
	s_cmp_lt_i32 s17, 64
	v_readlane_b32 s7, v255, 18
	v_readlane_b32 s6, v255, 17
	s_cselect_b32 s49, s13, s7
	s_cselect_b32 s48, s12, s6
	s_cselect_b32 s27, s15, s7
	s_cselect_b32 s26, s14, s6
	s_min_i32 s6, s17, 64
	s_ashr_i32 s6, s6, 4
	s_mul_hi_i32 s7, s6, 0xc000
	s_mul_i32 s6, s6, 0xc000
	s_add_u32 s6, s22, s6
	s_mov_b32 s2, s68
	s_mov_b32 s3, s57
	s_addc_u32 s7, s23, s7
	s_add_u32 s50, s6, 0xa000
	s_addc_u32 s51, s7, 0
	s_lshl_b32 s6, s17, 8
	s_lshl_b32 s3, s3, 6
	s_lshl_b32 s7, s30, 8
	s_lshl_b32 s2, s2, 5
	s_add_i32 s3, s3, s6
	s_add_i32 s2, s2, s7
	v_add_u32_e32 v160, s3, v167
	v_lshl_add_u32 v150, v166, 2, s2
	v_lshlrev_b32_e32 v164, 2, v150
	v_lshl_add_u32 v170, v160, 13, v164
	v_add_u32_e32 v171, 0x20000, v170
	v_add_u32_e32 v172, 0x40000, v170
	v_add_u32_e32 v173, 0x60000, v170
	v_lshlrev_b32_e32 v161, 3, v160
	global_load_dwordx2 v[174:175], v161, s[18:19]
	global_load_dwordx2 v[176:177], v161, s[18:19] offset:128
	global_load_dwordx2 v[178:179], v161, s[18:19] offset:256
	global_load_dwordx2 v[180:181], v161, s[18:19] offset:384
	global_load_dwordx2 v[182:183], v161, s[18:19] offset:1024
	global_load_dwordx2 v[184:185], v161, s[18:19] offset:1152
	global_load_dwordx2 v[186:187], v161, s[18:19] offset:1280
	global_load_dwordx2 v[188:189], v161, s[18:19] offset:1408
	global_load_dwordx4 v[118:121], v164, s[50:51]
	global_load_dwordx4 v[122:125], v164, s[24:25]
	global_load_dwordx4 v[126:129], v164, s[36:37]
	global_load_dwordx4 v[148:151], v170, s[48:49]
	global_load_dwordx4 v[152:155], v171, s[48:49]
	global_load_dwordx4 v[156:159], v172, s[48:49]
	global_load_dwordx4 v[160:163], v173, s[48:49]
	v_add_u32_e32 v165, 0x100000, v170
	global_load_dwordx4 v[190:193], v165, s[48:49]
	v_add_u32_e32 v165, 0x100000, v171
	global_load_dwordx4 v[194:197], v165, s[48:49]
	v_add_u32_e32 v165, 0x100000, v172
	global_load_dwordx4 v[198:201], v165, s[48:49]
	v_add_u32_e32 v165, 0x100000, v173
	global_load_dwordx4 v[202:205], v165, s[48:49]
	s_waitcnt vmcnt(0)
	v_sub_f32_e32 v151, v151, v174
	v_sub_f32_e32 v150, v150, v174
	v_sub_f32_e32 v149, v149, v174
	v_sub_f32_e32 v148, v148, v174
	v_pk_mul_f32 v[148:149], v[174:175], v[148:149] op_sel:[1,0]
	v_pk_mul_f32 v[150:151], v[174:175], v[150:151] op_sel:[1,0]
	v_pk_fma_f32 v[148:149], v[122:123], v[148:149], v[126:127]
	v_pk_fma_f32 v[150:151], v[124:125], v[150:151], v[128:129]
	v_pk_mul_f32 v[148:149], v[148:149], s[88:89] op_sel_hi:[1,0]
	v_pk_mul_f32 v[150:151], v[150:151], s[88:89] op_sel_hi:[1,0]
	v_pk_fma_f32 v[138:139], v[138:139], v[118:119], v[148:149]
	v_pk_fma_f32 v[140:141], v[140:141], v[120:121], v[150:151]
	global_store_dwordx4 v170, v[138:141], s[26:27]
	s_nop 1
	global_load_dwordx4 v[138:141], v170, s[48:49] offset:64
	v_sub_f32_e32 v155, v155, v176
	v_sub_f32_e32 v154, v154, v176
	v_sub_f32_e32 v153, v153, v176
	v_sub_f32_e32 v152, v152, v176
	v_pk_mul_f32 v[152:153], v[176:177], v[152:153] op_sel:[1,0]
	v_pk_mul_f32 v[154:155], v[176:177], v[154:155] op_sel:[1,0]
	v_pk_fma_f32 v[152:153], v[122:123], v[152:153], v[126:127]
	v_pk_fma_f32 v[154:155], v[124:125], v[154:155], v[128:129]
	v_pk_mul_f32 v[152:153], v[152:153], s[88:89] op_sel_hi:[1,0]
	v_pk_mul_f32 v[154:155], v[154:155], s[88:89] op_sel_hi:[1,0]
	v_pk_fma_f32 v[134:135], v[134:135], v[118:119], v[152:153]
	v_pk_fma_f32 v[136:137], v[136:137], v[120:121], v[154:155]
	global_store_dwordx4 v171, v[134:137], s[26:27]
	s_nop 1
	global_load_dwordx4 v[134:137], v171, s[48:49] offset:64
	v_sub_f32_e32 v159, v159, v178
	v_sub_f32_e32 v158, v158, v178
	v_sub_f32_e32 v157, v157, v178
	v_sub_f32_e32 v156, v156, v178
	v_pk_mul_f32 v[156:157], v[178:179], v[156:157] op_sel:[1,0]
	v_pk_mul_f32 v[158:159], v[178:179], v[158:159] op_sel:[1,0]
	v_pk_fma_f32 v[156:157], v[122:123], v[156:157], v[126:127]
	v_pk_fma_f32 v[158:159], v[124:125], v[158:159], v[128:129]
	v_pk_mul_f32 v[156:157], v[156:157], s[88:89] op_sel_hi:[1,0]
	v_pk_mul_f32 v[158:159], v[158:159], s[88:89] op_sel_hi:[1,0]
	v_pk_fma_f32 v[130:131], v[130:131], v[118:119], v[156:157]
	v_pk_fma_f32 v[132:133], v[132:133], v[120:121], v[158:159]
	global_store_dwordx4 v172, v[130:133], s[26:27]
	s_nop 1
	global_load_dwordx4 v[130:133], v172, s[48:49] offset:64
	v_sub_f32_e32 v163, v163, v180
	v_sub_f32_e32 v162, v162, v180
	v_sub_f32_e32 v161, v161, v180
	v_sub_f32_e32 v160, v160, v180
	v_pk_mul_f32 v[160:161], v[180:181], v[160:161] op_sel:[1,0]
	v_pk_mul_f32 v[162:163], v[180:181], v[162:163] op_sel:[1,0]
	v_pk_fma_f32 v[160:161], v[122:123], v[160:161], v[126:127]
	v_pk_fma_f32 v[162:163], v[124:125], v[162:163], v[128:129]
	v_pk_mul_f32 v[160:161], v[160:161], s[88:89] op_sel_hi:[1,0]
	v_pk_mul_f32 v[162:163], v[162:163], s[88:89] op_sel_hi:[1,0]
	v_pk_fma_f32 v[114:115], v[114:115], v[118:119], v[160:161]
	v_pk_fma_f32 v[116:117], v[116:117], v[120:121], v[162:163]
	global_store_dwordx4 v173, v[114:117], s[26:27]
	s_nop 1
	global_load_dwordx4 v[114:117], v173, s[48:49] offset:64
	v_sub_f32_e32 v193, v193, v182
	v_sub_f32_e32 v192, v192, v182
	v_sub_f32_e32 v191, v191, v182
	v_sub_f32_e32 v190, v190, v182
	v_pk_mul_f32 v[190:191], v[182:183], v[190:191] op_sel:[1,0]
	v_pk_mul_f32 v[192:193], v[182:183], v[192:193] op_sel:[1,0]
	v_pk_fma_f32 v[190:191], v[122:123], v[190:191], v[126:127]
	v_pk_fma_f32 v[192:193], v[124:125], v[192:193], v[128:129]
	v_pk_mul_f32 v[190:191], v[190:191], s[88:89] op_sel_hi:[1,0]
	v_pk_mul_f32 v[192:193], v[192:193], s[88:89] op_sel_hi:[1,0]
	v_pk_fma_f32 v[110:111], v[110:111], v[118:119], v[190:191]
	v_pk_fma_f32 v[112:113], v[112:113], v[120:121], v[192:193]
	v_add_u32_e32 v165, 0x100000, v170
	global_store_dwordx4 v165, v[110:113], s[26:27]
	s_nop 1
	global_load_dwordx4 v[110:113], v165, s[48:49] offset:64
	v_sub_f32_e32 v197, v197, v184
	v_sub_f32_e32 v196, v196, v184
	v_sub_f32_e32 v195, v195, v184
	v_sub_f32_e32 v194, v194, v184
	v_pk_mul_f32 v[194:195], v[184:185], v[194:195] op_sel:[1,0]
	v_pk_mul_f32 v[196:197], v[184:185], v[196:197] op_sel:[1,0]
	v_pk_fma_f32 v[194:195], v[122:123], v[194:195], v[126:127]
	v_pk_fma_f32 v[196:197], v[124:125], v[196:197], v[128:129]
	v_pk_mul_f32 v[194:195], v[194:195], s[88:89] op_sel_hi:[1,0]
	v_pk_mul_f32 v[196:197], v[196:197], s[88:89] op_sel_hi:[1,0]
	v_pk_fma_f32 v[106:107], v[106:107], v[118:119], v[194:195]
	v_pk_fma_f32 v[108:109], v[108:109], v[120:121], v[196:197]
	v_add_u32_e32 v165, 0x100000, v171
	global_store_dwordx4 v165, v[106:109], s[26:27]
	s_nop 1
	global_load_dwordx4 v[106:109], v165, s[48:49] offset:64
	v_sub_f32_e32 v201, v201, v186
	v_sub_f32_e32 v200, v200, v186
	v_sub_f32_e32 v199, v199, v186
	v_sub_f32_e32 v198, v198, v186
	v_pk_mul_f32 v[198:199], v[186:187], v[198:199] op_sel:[1,0]
	v_pk_mul_f32 v[200:201], v[186:187], v[200:201] op_sel:[1,0]
	v_pk_fma_f32 v[198:199], v[122:123], v[198:199], v[126:127]
	v_pk_fma_f32 v[200:201], v[124:125], v[200:201], v[128:129]
	v_pk_mul_f32 v[198:199], v[198:199], s[88:89] op_sel_hi:[1,0]
	v_pk_mul_f32 v[200:201], v[200:201], s[88:89] op_sel_hi:[1,0]
	v_pk_fma_f32 v[102:103], v[102:103], v[118:119], v[198:199]
	v_pk_fma_f32 v[104:105], v[104:105], v[120:121], v[200:201]
	v_add_u32_e32 v165, 0x100000, v172
	global_store_dwordx4 v165, v[102:105], s[26:27]
	s_nop 1
	global_load_dwordx4 v[102:105], v165, s[48:49] offset:64
	v_sub_f32_e32 v205, v205, v188
	v_sub_f32_e32 v204, v204, v188
	v_sub_f32_e32 v203, v203, v188
	v_sub_f32_e32 v202, v202, v188
	v_pk_mul_f32 v[202:203], v[188:189], v[202:203] op_sel:[1,0]
	v_pk_mul_f32 v[204:205], v[188:189], v[204:205] op_sel:[1,0]
	v_pk_fma_f32 v[202:203], v[122:123], v[202:203], v[126:127]
	v_pk_fma_f32 v[204:205], v[124:125], v[204:205], v[128:129]
	v_pk_mul_f32 v[202:203], v[202:203], s[88:89] op_sel_hi:[1,0]
	v_pk_mul_f32 v[204:205], v[204:205], s[88:89] op_sel_hi:[1,0]
	v_pk_fma_f32 v[98:99], v[98:99], v[118:119], v[202:203]
	v_pk_fma_f32 v[100:101], v[100:101], v[120:121], v[204:205]
	v_add_u32_e32 v165, 0x100000, v173
	global_store_dwordx4 v165, v[98:101], s[26:27]
	s_nop 1
	global_load_dwordx4 v[98:101], v165, s[48:49] offset:64
	global_load_dwordx4 v[118:121], v164, s[50:51] offset:64
	global_load_dwordx4 v[122:125], v164, s[24:25] offset:64
	global_load_dwordx4 v[126:129], v164, s[36:37] offset:64
	s_waitcnt vmcnt(0)
	v_sub_f32_e32 v141, v141, v174
	v_sub_f32_e32 v140, v140, v174
	v_sub_f32_e32 v139, v139, v174
	v_sub_f32_e32 v138, v138, v174
	v_pk_mul_f32 v[138:139], v[174:175], v[138:139] op_sel:[1,0]
	v_pk_mul_f32 v[140:141], v[174:175], v[140:141] op_sel:[1,0]
	v_pk_fma_f32 v[138:139], v[122:123], v[138:139], v[126:127]
	v_pk_fma_f32 v[140:141], v[124:125], v[140:141], v[128:129]
	v_pk_mul_f32 v[138:139], v[138:139], s[88:89] op_sel_hi:[1,0]
	v_pk_mul_f32 v[140:141], v[140:141], s[88:89] op_sel_hi:[1,0]
	v_pk_fma_f32 v[94:95], v[94:95], v[118:119], v[138:139]
	v_pk_fma_f32 v[96:97], v[96:97], v[120:121], v[140:141]
	global_store_dwordx4 v170, v[94:97], s[26:27] offset:64
	s_nop 1
	global_load_dwordx4 v[94:97], v170, s[48:49] offset:512
	v_sub_f32_e32 v137, v137, v176
	v_sub_f32_e32 v136, v136, v176
	v_sub_f32_e32 v135, v135, v176
	v_sub_f32_e32 v134, v134, v176
	v_pk_mul_f32 v[134:135], v[176:177], v[134:135] op_sel:[1,0]
	v_pk_mul_f32 v[136:137], v[176:177], v[136:137] op_sel:[1,0]
	v_pk_fma_f32 v[134:135], v[122:123], v[134:135], v[126:127]
	v_pk_fma_f32 v[136:137], v[124:125], v[136:137], v[128:129]
	v_pk_mul_f32 v[134:135], v[134:135], s[88:89] op_sel_hi:[1,0]
	v_pk_mul_f32 v[136:137], v[136:137], s[88:89] op_sel_hi:[1,0]
	v_pk_fma_f32 v[90:91], v[90:91], v[118:119], v[134:135]
	v_pk_fma_f32 v[92:93], v[92:93], v[120:121], v[136:137]
	global_store_dwordx4 v171, v[90:93], s[26:27] offset:64
	s_nop 1
	global_load_dwordx4 v[90:93], v171, s[48:49] offset:512
	v_sub_f32_e32 v133, v133, v178
	v_sub_f32_e32 v132, v132, v178
	v_sub_f32_e32 v131, v131, v178
	v_sub_f32_e32 v130, v130, v178
	v_pk_mul_f32 v[130:131], v[178:179], v[130:131] op_sel:[1,0]
	v_pk_mul_f32 v[132:133], v[178:179], v[132:133] op_sel:[1,0]
	v_pk_fma_f32 v[130:131], v[122:123], v[130:131], v[126:127]
	v_pk_fma_f32 v[132:133], v[124:125], v[132:133], v[128:129]
	v_pk_mul_f32 v[130:131], v[130:131], s[88:89] op_sel_hi:[1,0]
	v_pk_mul_f32 v[132:133], v[132:133], s[88:89] op_sel_hi:[1,0]
	v_pk_fma_f32 v[86:87], v[86:87], v[118:119], v[130:131]
	v_pk_fma_f32 v[88:89], v[88:89], v[120:121], v[132:133]
	global_store_dwordx4 v172, v[86:89], s[26:27] offset:64
	s_nop 1
	global_load_dwordx4 v[86:89], v172, s[48:49] offset:512
	v_sub_f32_e32 v117, v117, v180
	v_sub_f32_e32 v116, v116, v180
	v_sub_f32_e32 v115, v115, v180
	v_sub_f32_e32 v114, v114, v180
	v_pk_mul_f32 v[114:115], v[180:181], v[114:115] op_sel:[1,0]
	v_pk_mul_f32 v[116:117], v[180:181], v[116:117] op_sel:[1,0]
	v_pk_fma_f32 v[114:115], v[122:123], v[114:115], v[126:127]
	v_pk_fma_f32 v[116:117], v[124:125], v[116:117], v[128:129]
	v_pk_mul_f32 v[114:115], v[114:115], s[88:89] op_sel_hi:[1,0]
	v_pk_mul_f32 v[116:117], v[116:117], s[88:89] op_sel_hi:[1,0]
	v_pk_fma_f32 v[82:83], v[82:83], v[118:119], v[114:115]
	v_pk_fma_f32 v[84:85], v[84:85], v[120:121], v[116:117]
	global_store_dwordx4 v173, v[82:85], s[26:27] offset:64
	s_nop 1
	global_load_dwordx4 v[82:85], v173, s[48:49] offset:512
	v_sub_f32_e32 v113, v113, v182
	v_sub_f32_e32 v112, v112, v182
	v_sub_f32_e32 v111, v111, v182
	v_sub_f32_e32 v110, v110, v182
	v_pk_mul_f32 v[110:111], v[182:183], v[110:111] op_sel:[1,0]
	v_pk_mul_f32 v[112:113], v[182:183], v[112:113] op_sel:[1,0]
	v_pk_fma_f32 v[110:111], v[122:123], v[110:111], v[126:127]
	v_pk_fma_f32 v[112:113], v[124:125], v[112:113], v[128:129]
	v_pk_mul_f32 v[110:111], v[110:111], s[88:89] op_sel_hi:[1,0]
	v_pk_mul_f32 v[112:113], v[112:113], s[88:89] op_sel_hi:[1,0]
	v_pk_fma_f32 v[78:79], v[78:79], v[118:119], v[110:111]
	v_pk_fma_f32 v[80:81], v[80:81], v[120:121], v[112:113]
	v_add_u32_e32 v165, 0x100000, v170
	global_store_dwordx4 v165, v[78:81], s[26:27] offset:64
	s_nop 1
	global_load_dwordx4 v[78:81], v165, s[48:49] offset:512
	v_sub_f32_e32 v109, v109, v184
	v_sub_f32_e32 v108, v108, v184
	v_sub_f32_e32 v107, v107, v184
	v_sub_f32_e32 v106, v106, v184
	v_pk_mul_f32 v[106:107], v[184:185], v[106:107] op_sel:[1,0]
	v_pk_mul_f32 v[108:109], v[184:185], v[108:109] op_sel:[1,0]
	v_pk_fma_f32 v[106:107], v[122:123], v[106:107], v[126:127]
	v_pk_fma_f32 v[108:109], v[124:125], v[108:109], v[128:129]
	v_pk_mul_f32 v[106:107], v[106:107], s[88:89] op_sel_hi:[1,0]
	v_pk_mul_f32 v[108:109], v[108:109], s[88:89] op_sel_hi:[1,0]
	v_pk_fma_f32 v[74:75], v[74:75], v[118:119], v[106:107]
	v_pk_fma_f32 v[76:77], v[76:77], v[120:121], v[108:109]
	v_add_u32_e32 v165, 0x100000, v171
	global_store_dwordx4 v165, v[74:77], s[26:27] offset:64
	s_nop 1
	global_load_dwordx4 v[74:77], v165, s[48:49] offset:512
	v_sub_f32_e32 v105, v105, v186
	v_sub_f32_e32 v104, v104, v186
	v_sub_f32_e32 v103, v103, v186
	v_sub_f32_e32 v102, v102, v186
	v_pk_mul_f32 v[102:103], v[186:187], v[102:103] op_sel:[1,0]
	v_pk_mul_f32 v[104:105], v[186:187], v[104:105] op_sel:[1,0]
	v_pk_fma_f32 v[102:103], v[122:123], v[102:103], v[126:127]
	v_pk_fma_f32 v[104:105], v[124:125], v[104:105], v[128:129]
	v_pk_mul_f32 v[102:103], v[102:103], s[88:89] op_sel_hi:[1,0]
	v_pk_mul_f32 v[104:105], v[104:105], s[88:89] op_sel_hi:[1,0]
	v_pk_fma_f32 v[70:71], v[70:71], v[118:119], v[102:103]
	v_pk_fma_f32 v[72:73], v[72:73], v[120:121], v[104:105]
	v_add_u32_e32 v165, 0x100000, v172
	global_store_dwordx4 v165, v[70:73], s[26:27] offset:64
	s_nop 1
	global_load_dwordx4 v[70:73], v165, s[48:49] offset:512
	v_sub_f32_e32 v101, v101, v188
	v_sub_f32_e32 v100, v100, v188
	v_sub_f32_e32 v99, v99, v188
	v_sub_f32_e32 v98, v98, v188
	v_pk_mul_f32 v[98:99], v[188:189], v[98:99] op_sel:[1,0]
	v_pk_mul_f32 v[100:101], v[188:189], v[100:101] op_sel:[1,0]
	v_pk_fma_f32 v[98:99], v[122:123], v[98:99], v[126:127]
	v_pk_fma_f32 v[100:101], v[124:125], v[100:101], v[128:129]
	v_pk_mul_f32 v[98:99], v[98:99], s[88:89] op_sel_hi:[1,0]
	v_pk_mul_f32 v[100:101], v[100:101], s[88:89] op_sel_hi:[1,0]
	v_pk_fma_f32 v[66:67], v[66:67], v[118:119], v[98:99]
	v_pk_fma_f32 v[68:69], v[68:69], v[120:121], v[100:101]
	v_add_u32_e32 v165, 0x100000, v173
	global_store_dwordx4 v165, v[66:69], s[26:27] offset:64
	s_nop 1
	global_load_dwordx4 v[66:69], v165, s[48:49] offset:512
	global_load_dwordx4 v[118:121], v164, s[50:51] offset:512
	global_load_dwordx4 v[122:125], v164, s[24:25] offset:512
	global_load_dwordx4 v[126:129], v164, s[36:37] offset:512
	s_waitcnt vmcnt(0)
	v_sub_f32_e32 v97, v97, v174
	v_sub_f32_e32 v96, v96, v174
	v_sub_f32_e32 v95, v95, v174
	v_sub_f32_e32 v94, v94, v174
	v_pk_mul_f32 v[94:95], v[174:175], v[94:95] op_sel:[1,0]
	v_pk_mul_f32 v[96:97], v[174:175], v[96:97] op_sel:[1,0]
	v_pk_fma_f32 v[94:95], v[122:123], v[94:95], v[126:127]
	v_pk_fma_f32 v[96:97], v[124:125], v[96:97], v[128:129]
	v_pk_mul_f32 v[94:95], v[94:95], s[88:89] op_sel_hi:[1,0]
	v_pk_mul_f32 v[96:97], v[96:97], s[88:89] op_sel_hi:[1,0]
	v_pk_fma_f32 v[62:63], v[62:63], v[118:119], v[94:95]
	v_pk_fma_f32 v[64:65], v[64:65], v[120:121], v[96:97]
	global_store_dwordx4 v170, v[62:65], s[26:27] offset:512
	s_nop 1
	global_load_dwordx4 v[62:65], v170, s[48:49] offset:576
	v_sub_f32_e32 v93, v93, v176
	v_sub_f32_e32 v92, v92, v176
	v_sub_f32_e32 v91, v91, v176
	v_sub_f32_e32 v90, v90, v176
	v_pk_mul_f32 v[90:91], v[176:177], v[90:91] op_sel:[1,0]
	v_pk_mul_f32 v[92:93], v[176:177], v[92:93] op_sel:[1,0]
	v_pk_fma_f32 v[90:91], v[122:123], v[90:91], v[126:127]
	v_pk_fma_f32 v[92:93], v[124:125], v[92:93], v[128:129]
	v_pk_mul_f32 v[90:91], v[90:91], s[88:89] op_sel_hi:[1,0]
	v_pk_mul_f32 v[92:93], v[92:93], s[88:89] op_sel_hi:[1,0]
	v_pk_fma_f32 v[58:59], v[58:59], v[118:119], v[90:91]
	v_pk_fma_f32 v[60:61], v[60:61], v[120:121], v[92:93]
	global_store_dwordx4 v171, v[58:61], s[26:27] offset:512
	s_nop 1
	global_load_dwordx4 v[58:61], v171, s[48:49] offset:576
	v_sub_f32_e32 v89, v89, v178
	v_sub_f32_e32 v88, v88, v178
	v_sub_f32_e32 v87, v87, v178
	v_sub_f32_e32 v86, v86, v178
	v_pk_mul_f32 v[86:87], v[178:179], v[86:87] op_sel:[1,0]
	v_pk_mul_f32 v[88:89], v[178:179], v[88:89] op_sel:[1,0]
	v_pk_fma_f32 v[86:87], v[122:123], v[86:87], v[126:127]
	v_pk_fma_f32 v[88:89], v[124:125], v[88:89], v[128:129]
	v_pk_mul_f32 v[86:87], v[86:87], s[88:89] op_sel_hi:[1,0]
	v_pk_mul_f32 v[88:89], v[88:89], s[88:89] op_sel_hi:[1,0]
	v_pk_fma_f32 v[54:55], v[54:55], v[118:119], v[86:87]
	v_pk_fma_f32 v[56:57], v[56:57], v[120:121], v[88:89]
	global_store_dwordx4 v172, v[54:57], s[26:27] offset:512
	s_nop 1
	global_load_dwordx4 v[54:57], v172, s[48:49] offset:576
	v_sub_f32_e32 v85, v85, v180
	v_sub_f32_e32 v84, v84, v180
	v_sub_f32_e32 v83, v83, v180
	v_sub_f32_e32 v82, v82, v180
	v_pk_mul_f32 v[82:83], v[180:181], v[82:83] op_sel:[1,0]
	v_pk_mul_f32 v[84:85], v[180:181], v[84:85] op_sel:[1,0]
	v_pk_fma_f32 v[82:83], v[122:123], v[82:83], v[126:127]
	v_pk_fma_f32 v[84:85], v[124:125], v[84:85], v[128:129]
	v_pk_mul_f32 v[82:83], v[82:83], s[88:89] op_sel_hi:[1,0]
	v_pk_mul_f32 v[84:85], v[84:85], s[88:89] op_sel_hi:[1,0]
	v_pk_fma_f32 v[50:51], v[50:51], v[118:119], v[82:83]
	v_pk_fma_f32 v[52:53], v[52:53], v[120:121], v[84:85]
	global_store_dwordx4 v173, v[50:53], s[26:27] offset:512
	s_nop 1
	global_load_dwordx4 v[50:53], v173, s[48:49] offset:576
	v_sub_f32_e32 v81, v81, v182
	v_sub_f32_e32 v80, v80, v182
	v_sub_f32_e32 v79, v79, v182
	v_sub_f32_e32 v78, v78, v182
	v_pk_mul_f32 v[78:79], v[182:183], v[78:79] op_sel:[1,0]
	v_pk_mul_f32 v[80:81], v[182:183], v[80:81] op_sel:[1,0]
	v_pk_fma_f32 v[78:79], v[122:123], v[78:79], v[126:127]
	v_pk_fma_f32 v[80:81], v[124:125], v[80:81], v[128:129]
	v_pk_mul_f32 v[78:79], v[78:79], s[88:89] op_sel_hi:[1,0]
	v_pk_mul_f32 v[80:81], v[80:81], s[88:89] op_sel_hi:[1,0]
	v_pk_fma_f32 v[46:47], v[46:47], v[118:119], v[78:79]
	v_pk_fma_f32 v[48:49], v[48:49], v[120:121], v[80:81]
	v_add_u32_e32 v165, 0x100000, v170
	global_store_dwordx4 v165, v[46:49], s[26:27] offset:512
	s_nop 1
	global_load_dwordx4 v[46:49], v165, s[48:49] offset:576
	v_sub_f32_e32 v77, v77, v184
	v_sub_f32_e32 v76, v76, v184
	v_sub_f32_e32 v75, v75, v184
	v_sub_f32_e32 v74, v74, v184
	v_pk_mul_f32 v[74:75], v[184:185], v[74:75] op_sel:[1,0]
	v_pk_mul_f32 v[76:77], v[184:185], v[76:77] op_sel:[1,0]
	v_pk_fma_f32 v[74:75], v[122:123], v[74:75], v[126:127]
	v_pk_fma_f32 v[76:77], v[124:125], v[76:77], v[128:129]
	v_pk_mul_f32 v[74:75], v[74:75], s[88:89] op_sel_hi:[1,0]
	v_pk_mul_f32 v[76:77], v[76:77], s[88:89] op_sel_hi:[1,0]
	v_pk_fma_f32 v[42:43], v[42:43], v[118:119], v[74:75]
	v_pk_fma_f32 v[44:45], v[44:45], v[120:121], v[76:77]
	v_add_u32_e32 v165, 0x100000, v171
	global_store_dwordx4 v165, v[42:45], s[26:27] offset:512
	s_nop 1
	global_load_dwordx4 v[42:45], v165, s[48:49] offset:576
	v_sub_f32_e32 v73, v73, v186
	v_sub_f32_e32 v72, v72, v186
	v_sub_f32_e32 v71, v71, v186
	v_sub_f32_e32 v70, v70, v186
	v_pk_mul_f32 v[70:71], v[186:187], v[70:71] op_sel:[1,0]
	v_pk_mul_f32 v[72:73], v[186:187], v[72:73] op_sel:[1,0]
	v_pk_fma_f32 v[70:71], v[122:123], v[70:71], v[126:127]
	v_pk_fma_f32 v[72:73], v[124:125], v[72:73], v[128:129]
	v_pk_mul_f32 v[70:71], v[70:71], s[88:89] op_sel_hi:[1,0]
	v_pk_mul_f32 v[72:73], v[72:73], s[88:89] op_sel_hi:[1,0]
	v_pk_fma_f32 v[38:39], v[38:39], v[118:119], v[70:71]
	v_pk_fma_f32 v[40:41], v[40:41], v[120:121], v[72:73]
	v_add_u32_e32 v165, 0x100000, v172
	global_store_dwordx4 v165, v[38:41], s[26:27] offset:512
	s_nop 1
	global_load_dwordx4 v[38:41], v165, s[48:49] offset:576
	v_sub_f32_e32 v69, v69, v188
	v_sub_f32_e32 v68, v68, v188
	v_sub_f32_e32 v67, v67, v188
	v_sub_f32_e32 v66, v66, v188
	v_pk_mul_f32 v[66:67], v[188:189], v[66:67] op_sel:[1,0]
	v_pk_mul_f32 v[68:69], v[188:189], v[68:69] op_sel:[1,0]
	v_pk_fma_f32 v[66:67], v[122:123], v[66:67], v[126:127]
	v_pk_fma_f32 v[68:69], v[124:125], v[68:69], v[128:129]
	v_pk_mul_f32 v[66:67], v[66:67], s[88:89] op_sel_hi:[1,0]
	v_pk_mul_f32 v[68:69], v[68:69], s[88:89] op_sel_hi:[1,0]
	v_pk_fma_f32 v[34:35], v[34:35], v[118:119], v[66:67]
	v_pk_fma_f32 v[36:37], v[36:37], v[120:121], v[68:69]
	v_add_u32_e32 v165, 0x100000, v173
	global_store_dwordx4 v165, v[34:37], s[26:27] offset:512
	s_nop 1
	global_load_dwordx4 v[34:37], v165, s[48:49] offset:576
	global_load_dwordx4 v[118:121], v164, s[50:51] offset:576
	global_load_dwordx4 v[122:125], v164, s[24:25] offset:576
	global_load_dwordx4 v[126:129], v164, s[36:37] offset:576
	s_waitcnt vmcnt(0)
	v_sub_f32_e32 v65, v65, v174
	v_sub_f32_e32 v64, v64, v174
	v_sub_f32_e32 v63, v63, v174
	v_sub_f32_e32 v62, v62, v174
	v_pk_mul_f32 v[62:63], v[174:175], v[62:63] op_sel:[1,0]
	v_pk_mul_f32 v[64:65], v[174:175], v[64:65] op_sel:[1,0]
	v_pk_fma_f32 v[62:63], v[122:123], v[62:63], v[126:127]
	v_pk_fma_f32 v[64:65], v[124:125], v[64:65], v[128:129]
	v_pk_mul_f32 v[62:63], v[62:63], s[88:89] op_sel_hi:[1,0]
	v_pk_mul_f32 v[64:65], v[64:65], s[88:89] op_sel_hi:[1,0]
	v_pk_fma_f32 v[30:31], v[30:31], v[118:119], v[62:63]
	v_pk_fma_f32 v[32:33], v[32:33], v[120:121], v[64:65]
	global_store_dwordx4 v170, v[30:33], s[26:27] offset:576
	v_sub_f32_e32 v61, v61, v176
	v_sub_f32_e32 v60, v60, v176
	v_sub_f32_e32 v59, v59, v176
	v_sub_f32_e32 v58, v58, v176
	v_pk_mul_f32 v[58:59], v[176:177], v[58:59] op_sel:[1,0]
	v_pk_mul_f32 v[60:61], v[176:177], v[60:61] op_sel:[1,0]
	v_pk_fma_f32 v[58:59], v[122:123], v[58:59], v[126:127]
	v_pk_fma_f32 v[60:61], v[124:125], v[60:61], v[128:129]
	v_pk_mul_f32 v[58:59], v[58:59], s[88:89] op_sel_hi:[1,0]
	v_pk_mul_f32 v[60:61], v[60:61], s[88:89] op_sel_hi:[1,0]
	v_pk_fma_f32 v[26:27], v[26:27], v[118:119], v[58:59]
	v_pk_fma_f32 v[28:29], v[28:29], v[120:121], v[60:61]
	global_store_dwordx4 v171, v[26:29], s[26:27] offset:576
	v_sub_f32_e32 v57, v57, v178
	v_sub_f32_e32 v56, v56, v178
	v_sub_f32_e32 v55, v55, v178
	v_sub_f32_e32 v54, v54, v178
	v_pk_mul_f32 v[54:55], v[178:179], v[54:55] op_sel:[1,0]
	v_pk_mul_f32 v[56:57], v[178:179], v[56:57] op_sel:[1,0]
	v_pk_fma_f32 v[54:55], v[122:123], v[54:55], v[126:127]
	v_pk_fma_f32 v[56:57], v[124:125], v[56:57], v[128:129]
	v_pk_mul_f32 v[54:55], v[54:55], s[88:89] op_sel_hi:[1,0]
	v_pk_mul_f32 v[56:57], v[56:57], s[88:89] op_sel_hi:[1,0]
	v_pk_fma_f32 v[22:23], v[22:23], v[118:119], v[54:55]
	v_pk_fma_f32 v[24:25], v[24:25], v[120:121], v[56:57]
	global_store_dwordx4 v172, v[22:25], s[26:27] offset:576
	v_sub_f32_e32 v53, v53, v180
	v_sub_f32_e32 v52, v52, v180
	v_sub_f32_e32 v51, v51, v180
	v_sub_f32_e32 v50, v50, v180
	v_pk_mul_f32 v[50:51], v[180:181], v[50:51] op_sel:[1,0]
	v_pk_mul_f32 v[52:53], v[180:181], v[52:53] op_sel:[1,0]
	v_pk_fma_f32 v[50:51], v[122:123], v[50:51], v[126:127]
	v_pk_fma_f32 v[52:53], v[124:125], v[52:53], v[128:129]
	v_pk_mul_f32 v[50:51], v[50:51], s[88:89] op_sel_hi:[1,0]
	v_pk_mul_f32 v[52:53], v[52:53], s[88:89] op_sel_hi:[1,0]
	v_pk_fma_f32 v[18:19], v[18:19], v[118:119], v[50:51]
	v_pk_fma_f32 v[20:21], v[20:21], v[120:121], v[52:53]
	global_store_dwordx4 v173, v[18:21], s[26:27] offset:576
	v_sub_f32_e32 v49, v49, v182
	v_sub_f32_e32 v48, v48, v182
	v_sub_f32_e32 v47, v47, v182
	v_sub_f32_e32 v46, v46, v182
	v_pk_mul_f32 v[46:47], v[182:183], v[46:47] op_sel:[1,0]
	v_pk_mul_f32 v[48:49], v[182:183], v[48:49] op_sel:[1,0]
	v_pk_fma_f32 v[46:47], v[122:123], v[46:47], v[126:127]
	v_pk_fma_f32 v[48:49], v[124:125], v[48:49], v[128:129]
	v_pk_mul_f32 v[46:47], v[46:47], s[88:89] op_sel_hi:[1,0]
	v_pk_mul_f32 v[48:49], v[48:49], s[88:89] op_sel_hi:[1,0]
	v_pk_fma_f32 v[14:15], v[14:15], v[118:119], v[46:47]
	v_pk_fma_f32 v[16:17], v[16:17], v[120:121], v[48:49]
	v_add_u32_e32 v165, 0x100000, v170
	global_store_dwordx4 v165, v[14:17], s[26:27] offset:576
	v_sub_f32_e32 v45, v45, v184
	v_sub_f32_e32 v44, v44, v184
	v_sub_f32_e32 v43, v43, v184
	v_sub_f32_e32 v42, v42, v184
	v_pk_mul_f32 v[42:43], v[184:185], v[42:43] op_sel:[1,0]
	v_pk_mul_f32 v[44:45], v[184:185], v[44:45] op_sel:[1,0]
	v_pk_fma_f32 v[42:43], v[122:123], v[42:43], v[126:127]
	v_pk_fma_f32 v[44:45], v[124:125], v[44:45], v[128:129]
	v_pk_mul_f32 v[42:43], v[42:43], s[88:89] op_sel_hi:[1,0]
	v_pk_mul_f32 v[44:45], v[44:45], s[88:89] op_sel_hi:[1,0]
	v_pk_fma_f32 v[10:11], v[10:11], v[118:119], v[42:43]
	v_pk_fma_f32 v[12:13], v[12:13], v[120:121], v[44:45]
	v_add_u32_e32 v165, 0x100000, v171
	global_store_dwordx4 v165, v[10:13], s[26:27] offset:576
	v_sub_f32_e32 v41, v41, v186
	v_sub_f32_e32 v40, v40, v186
	v_sub_f32_e32 v39, v39, v186
	v_sub_f32_e32 v38, v38, v186
	v_pk_mul_f32 v[38:39], v[186:187], v[38:39] op_sel:[1,0]
	v_pk_mul_f32 v[40:41], v[186:187], v[40:41] op_sel:[1,0]
	v_pk_fma_f32 v[38:39], v[122:123], v[38:39], v[126:127]
	v_pk_fma_f32 v[40:41], v[124:125], v[40:41], v[128:129]
	v_pk_mul_f32 v[38:39], v[38:39], s[88:89] op_sel_hi:[1,0]
	v_pk_mul_f32 v[40:41], v[40:41], s[88:89] op_sel_hi:[1,0]
	v_pk_fma_f32 v[6:7], v[6:7], v[118:119], v[38:39]
	v_pk_fma_f32 v[8:9], v[8:9], v[120:121], v[40:41]
	v_add_u32_e32 v165, 0x100000, v172
	global_store_dwordx4 v165, v[6:9], s[26:27] offset:576
	v_sub_f32_e32 v37, v37, v188
	v_sub_f32_e32 v36, v36, v188
	v_sub_f32_e32 v35, v35, v188
	v_sub_f32_e32 v34, v34, v188
	v_pk_mul_f32 v[34:35], v[188:189], v[34:35] op_sel:[1,0]
	v_pk_mul_f32 v[36:37], v[188:189], v[36:37] op_sel:[1,0]
	v_pk_fma_f32 v[34:35], v[122:123], v[34:35], v[126:127]
	v_pk_fma_f32 v[36:37], v[124:125], v[36:37], v[128:129]
	v_pk_mul_f32 v[34:35], v[34:35], s[88:89] op_sel_hi:[1,0]
	v_pk_mul_f32 v[36:37], v[36:37], s[88:89] op_sel_hi:[1,0]
	v_pk_fma_f32 v[2:3], v[2:3], v[118:119], v[34:35]
	v_pk_fma_f32 v[4:5], v[4:5], v[120:121], v[36:37]
	v_add_u32_e32 v165, 0x100000, v173
	global_store_dwordx4 v165, v[2:5], s[26:27] offset:576
	s_mov_b64 s[2:3], -1
	s_and_b64 vcc, exec, s[4:5]
	s_cbranch_vccnz .LBB0_1801
	v_readlane_b32 s2, v255, 59
	v_readlane_b32 s3, v255, 60
	s_andn2_b64 vcc, exec, s[2:3]
	s_cbranch_vccnz .LBB0_1800
	s_barrier
	s_branch .LBB0_1800
